# static priority raise on the leading half (waves 0-3) instead of the trailing half, K-loop only
# speedup vs baseline: 1.0055x; 1.0055x over previous
; #define PG8_BAR __builtin_amdgcn_s_barrier()
; template <class Epi, class Sched, bool ALIGN_EPI = false, bool SP2 = false>
; __device__ __forceinline__ void gemm_phase(PG8_LAS unsigned char* lds, const Gemm g, const Sched& S, const Epi& E, const int wid_) {
;     ...
; #pragma unroll
;         for (int a = 0; a < 2; ++a)
; #pragma unroll
;             for (int b = 0; b < 2; ++b)
; #pragma unroll
;                 for (int m = 0; m < 4; ++m)
; #pragma unroll
;                     for (int n = 0; n < 2; ++n) acc[a][b][m][n] = (f32x4){0.f, 0.f, 0.f, 0.f};
;         cur = nxt; cA = nA; cB = nB; ++ui;
;         if constexpr (ALIGN_EPI) { if (wr == 1) PG8_BAR; }
.LBB0_379:
	s_add_u32 s49, s38, 0x100
	s_addc_u32 s62, s39, 0
	s_add_u32 s6, s98, 0x80
	s_addc_u32 s7, s99, 0
	s_mov_b32 s38, 0
	v_mov_b64_e32 v[0:1], 0
	v_mov_b64_e32 v[2:3], 0
	v_mov_b64_e32 v[4:5], 0
	v_mov_b64_e32 v[6:7], 0
	v_mov_b64_e32 v[8:9], 0
	v_mov_b64_e32 v[10:11], 0
	v_mov_b64_e32 v[12:13], 0
	v_mov_b64_e32 v[14:15], 0
	v_mov_b64_e32 v[16:17], 0
	v_mov_b64_e32 v[18:19], 0
	v_mov_b64_e32 v[20:21], 0
	v_mov_b64_e32 v[22:23], 0
	v_mov_b64_e32 v[24:25], 0
	v_mov_b64_e32 v[26:27], 0
	v_mov_b64_e32 v[28:29], 0
	v_mov_b64_e32 v[30:31], 0
	v_mov_b64_e32 v[32:33], 0
	v_mov_b64_e32 v[34:35], 0
	v_mov_b64_e32 v[36:37], 0
	v_mov_b64_e32 v[38:39], 0
	v_mov_b64_e32 v[40:41], 0
	v_mov_b64_e32 v[42:43], 0
	v_mov_b64_e32 v[44:45], 0
	v_mov_b64_e32 v[46:47], 0
	v_mov_b64_e32 v[48:49], 0
	v_mov_b64_e32 v[50:51], 0
	v_mov_b64_e32 v[52:53], 0
	v_mov_b64_e32 v[54:55], 0
	v_mov_b64_e32 v[56:57], 0
	v_mov_b64_e32 v[58:59], 0
	v_mov_b64_e32 v[60:61], 0
	v_mov_b64_e32 v[62:63], 0
	v_mov_b64_e32 v[64:65], 0
	v_mov_b64_e32 v[66:67], 0
	v_mov_b64_e32 v[68:69], 0
	v_mov_b64_e32 v[70:71], 0
	v_mov_b64_e32 v[72:73], 0
	v_mov_b64_e32 v[74:75], 0
	v_mov_b64_e32 v[76:77], 0
	v_mov_b64_e32 v[78:79], 0
	v_mov_b64_e32 v[80:81], 0
	v_mov_b64_e32 v[82:83], 0
	v_mov_b64_e32 v[84:85], 0
	v_mov_b64_e32 v[86:87], 0
	v_mov_b64_e32 v[88:89], 0
	v_mov_b64_e32 v[90:91], 0
	v_mov_b64_e32 v[92:93], 0
	v_mov_b64_e32 v[94:95], 0
	v_mov_b64_e32 v[96:97], 0
	v_mov_b64_e32 v[98:99], 0
	v_mov_b64_e32 v[100:101], 0
	v_mov_b64_e32 v[102:103], 0
	v_mov_b64_e32 v[104:105], 0
	v_mov_b64_e32 v[106:107], 0
	v_mov_b64_e32 v[108:109], 0
	v_mov_b64_e32 v[110:111], 0
	v_mov_b64_e32 v[112:113], 0
	v_mov_b64_e32 v[114:115], 0
	v_mov_b64_e32 v[116:117], 0
	v_mov_b64_e32 v[118:119], 0
	v_mov_b64_e32 v[120:121], 0
	v_mov_b64_e32 v[122:123], 0
	v_mov_b64_e32 v[124:125], 0
	v_mov_b64_e32 v[126:127], 0
	s_and_b64 vcc, exec, s[94:95]
	s_cbranch_vccz .Lprio_a
	s_setprio 1

; #define PG8_BAR __builtin_amdgcn_s_barrier()
; template <class Epi, class Sched, bool ALIGN_EPI = false, bool SP2 = false>
; __device__ __forceinline__ void gemm_phase(PG8_LAS unsigned char* lds, const Gemm g, const Sched& S, const Epi& E, const int wid_) {
;     ...
; #pragma unroll
;         for (int a = 0; a < 2; ++a)
; #pragma unroll
;             for (int b = 0; b < 2; ++b)
; #pragma unroll
;                 for (int m = 0; m < 4; ++m)
; #pragma unroll
;                     for (int n = 0; n < 2; ++n) acc[a][b][m][n] = (f32x4){0.f, 0.f, 0.f, 0.f};
;         cur = nxt; cA = nA; cB = nB; ++ui;
;         if constexpr (ALIGN_EPI) { if (wr == 1) PG8_BAR; }
.LBB0_613:
	s_add_u32 s11, s8, 0x100
	s_addc_u32 s76, s9, 0
	s_add_u32 s6, s38, 0x80
	s_addc_u32 s7, s39, 0
	s_mov_b32 s8, 0
	v_mov_b64_e32 v[0:1], 0
	v_mov_b64_e32 v[2:3], 0
	v_mov_b64_e32 v[4:5], 0
	v_mov_b64_e32 v[6:7], 0
	v_mov_b64_e32 v[8:9], 0
	v_mov_b64_e32 v[10:11], 0
	v_mov_b64_e32 v[12:13], 0
	v_mov_b64_e32 v[14:15], 0
	v_mov_b64_e32 v[16:17], 0
	v_mov_b64_e32 v[18:19], 0
	v_mov_b64_e32 v[20:21], 0
	v_mov_b64_e32 v[22:23], 0
	v_mov_b64_e32 v[24:25], 0
	v_mov_b64_e32 v[26:27], 0
	v_mov_b64_e32 v[28:29], 0
	v_mov_b64_e32 v[30:31], 0
	v_mov_b64_e32 v[32:33], 0
	v_mov_b64_e32 v[34:35], 0
	v_mov_b64_e32 v[36:37], 0
	v_mov_b64_e32 v[38:39], 0
	v_mov_b64_e32 v[40:41], 0
	v_mov_b64_e32 v[42:43], 0
	v_mov_b64_e32 v[44:45], 0
	v_mov_b64_e32 v[46:47], 0
	v_mov_b64_e32 v[48:49], 0
	v_mov_b64_e32 v[50:51], 0
	v_mov_b64_e32 v[52:53], 0
	v_mov_b64_e32 v[54:55], 0
	v_mov_b64_e32 v[56:57], 0
	v_mov_b64_e32 v[58:59], 0
	v_mov_b64_e32 v[60:61], 0
	v_mov_b64_e32 v[62:63], 0
	v_mov_b64_e32 v[64:65], 0
	v_mov_b64_e32 v[66:67], 0
	v_mov_b64_e32 v[68:69], 0
	v_mov_b64_e32 v[70:71], 0
	v_mov_b64_e32 v[72:73], 0
	v_mov_b64_e32 v[74:75], 0
	v_mov_b64_e32 v[76:77], 0
	v_mov_b64_e32 v[78:79], 0
	v_mov_b64_e32 v[80:81], 0
	v_mov_b64_e32 v[82:83], 0
	v_mov_b64_e32 v[84:85], 0
	v_mov_b64_e32 v[86:87], 0
	v_mov_b64_e32 v[88:89], 0
	v_mov_b64_e32 v[90:91], 0
	v_mov_b64_e32 v[92:93], 0
	v_mov_b64_e32 v[94:95], 0
	v_mov_b64_e32 v[96:97], 0
	v_mov_b64_e32 v[98:99], 0
	v_mov_b64_e32 v[100:101], 0
	v_mov_b64_e32 v[102:103], 0
	v_mov_b64_e32 v[108:109], 0
	v_mov_b64_e32 v[110:111], 0
	v_mov_b64_e32 v[116:117], 0
	v_mov_b64_e32 v[118:119], 0
	v_mov_b64_e32 v[120:121], 0
	v_mov_b64_e32 v[122:123], 0
	v_mov_b64_e32 v[128:129], 0
	v_mov_b64_e32 v[130:131], 0
	v_mov_b64_e32 v[136:137], 0
	v_mov_b64_e32 v[138:139], 0
	v_mov_b64_e32 v[140:141], 0
	v_mov_b64_e32 v[142:143], 0
	s_and_b64 vcc, exec, s[36:37]
	s_cbranch_vccz .Lprio_b
	s_setprio 1
